# pair-scoped P1->P2 barrier plus a one-time 4 us start stagger between the four XCD pairs
# speedup vs baseline: 1.0080x; 1.0080x over previous
; #define LAS __attribute__((address_space(3)))
; __global__ void __launch_bounds__(NWAVES * 64, 2) mk_fwd(Args a) {
;     ...
;     for (int l = 0; l < NLAYER; ++l) {
;         unsigned char* wl = ws + WS_W + (size_t)l * W_LAYER;
; #pragma unroll 1
;         for (int rep1 = 0; rep1 < REP_P1; ++rep1) {
;             pg8::Gemm g{XB, (const bf16u*)(wl + WL_IN), NTOK, INW, DMOD}; int bxp = bx; asm volatile("" : "+s"(bxp)); pg8::StaticOrder S; S.init(NTOK, INW, G, bxp);
;             pg8::Unit u0; int pm0 = -1; if (S.next(0, u0)) pm0 = u0.pm;
;             { int tt_ = threadIdx.x; asm volatile("" : "+v"(tt_)); if (pm0 >= 0 && tt_ < 256) ((LAS float*)(L + RING_BYTES))[tt_] = pg8::row_rstd(ssqA, pm0 * 256 + tt_); }
;             __syncthreads();
;             pg8::EpiProj E{Qb, BUFE, ssqA, rope, attn_body::C2, pm0, (const LAS float*)(L + RING_BYTES)};
;             pg8::gemm_phase<pg8::EpiProj, pg8::StaticOrder, true, true>(L, g, S, E);
;     ...
;                 const int nwg5 = (NTOK / 256) * (2 * DFF / 256), rem = nwg5 % G;
;                 const bool light = (rem == 0) || (bxp >= rem);
;                 if (light) { int tc_ = threadIdx.x; asm volatile("" : "+v"(tc_)); const int lnc = tc_ & 63; const int nl = (rem == 0) ? G : G - rem, li = (rem == 0) ? bxp : bxp - rem;
.LBB0_135:
	v_writelane_b32 v255, s72, 2
	s_nop 1
	v_writelane_b32 v255, s73, 3
	s_or_b64 exec, exec, s[2:3]
	s_add_u32 s0, s42, 0x100000
	s_addc_u32 s1, s43, 0
	v_writelane_b32 v255, s0, 4
	v_readlane_b32 s4, v253, 38
	s_mov_b32 s91, 0
	v_writelane_b32 v255, s1, 5
	s_add_u32 s0, s42, 0x200000
	s_addc_u32 s1, s43, 0
	s_add_u32 s82, s42, 0x9e00000
	s_addc_u32 s83, s43, 0
	s_add_u32 s6, s42, 0xbe00000
	v_writelane_b32 v255, s0, 6
	s_addc_u32 s7, s43, 0
	v_mov_b32_e32 v245, 0x358637bd
	v_writelane_b32 v255, s1, 7
	s_add_u32 s0, s42, 0xde00000
	v_writelane_b32 v255, s0, 8
	s_addc_u32 s0, s43, 0
	v_writelane_b32 v255, s0, 9
	s_add_u32 s0, s42, 0xfe00000
	v_writelane_b32 v255, s0, 10
	s_addc_u32 s0, s43, 0
	s_add_u32 s28, s42, 0x11e00000
	s_addc_u32 s29, s43, 0
	s_add_u32 s30, s42, 0x13e00000
	s_addc_u32 s31, s43, 0
	v_writelane_b32 v255, s0, 11
	s_add_u32 s0, s42, 0x17e00000
	s_addc_u32 s1, s43, 0
	v_writelane_b32 v255, s0, 12
	s_movk_i32 s61, 0x2000
	v_mov_b32_e32 v1, 0
	v_writelane_b32 v255, s1, 13
	s_add_u32 s0, s42, 0x19e00000
	s_addc_u32 s1, s43, 0
	s_add_u32 s14, s42, 0x1be00000
	s_addc_u32 s15, s43, 0
	s_add_u32 s86, s42, 0x1de00000
	s_addc_u32 s87, s43, 0
	s_ashr_i32 s79, s80, 31
	v_writelane_b32 v255, s0, 14
	s_cmpk_eq_i32 s80, 0x100
	s_mov_b32 s88, 0x8000
	v_writelane_b32 v255, s1, 15
	s_cselect_b64 s[0:1], -1, 0
	v_writelane_b32 v255, s0, 16
	s_lshl_b32 s89, s80, 2
	s_mov_b32 s27, 0xa000
	v_writelane_b32 v255, s1, 17
	s_abs_i32 s0, s80
	s_waitcnt lgkmcnt(0)
	v_cvt_f32_u32_e32 v0, s0
	s_lshl_b32 s1, s4, 5
	v_writelane_b32 v255, s1, 18
	s_sub_i32 s1, 0, s0
	v_rcp_iflag_f32_e32 v0, v0
	s_mov_b32 s26, 0xc000
	v_mov_b32_e32 v234, 1
	s_movk_i32 s10, 0x3ff
	v_mul_f32_e32 v0, 0x4f7ffffe, v0
	v_cvt_u32_f32_e32 v0, v0
	v_mov_b64_e32 v[236:237], 0x800
	v_mov_b32_e32 v235, 0x3e38aa3b
	v_mov_b32_e32 v248, 0xff800000
	v_readfirstlane_b32 s2, v0
	s_mul_i32 s1, s1, s2
	s_mul_hi_u32 s1, s2, s1
	s_add_i32 s2, s2, s1
	s_mul_hi_u32 s1, s2, 0x580
	s_mul_i32 s1, s1, s0
	s_sub_i32 s1, 0x580, s1
	s_sub_i32 s2, s1, s0
	s_cmp_ge_u32 s1, s0
	s_cselect_b32 s1, s2, s1
	s_sub_i32 s2, s1, s0
	s_cmp_ge_u32 s1, s0
	s_cselect_b32 s5, s2, s1
	s_cmp_eq_u32 s5, 0
	s_cselect_b64 s[2:3], -1, 0
	s_sub_i32 s0, s80, s5
	s_lshl_b32 s0, s0, 3
	v_writelane_b32 v255, s0, 19
	s_lshl_b32 s0, s80, 4
	v_writelane_b32 v255, s0, 20
	s_lshl_b32 s0, s4, 6
	s_lshl_b32 s1, s5, 9
	s_sub_i32 s8, s0, s1
	s_sub_i32 s0, s34, s1
	v_writelane_b32 v255, s0, 21
	s_lshl_b32 s0, s4, 2
	s_lshl_b32 s1, s5, 5
	s_sub_i32 s0, s0, s1
	v_writelane_b32 v255, s0, 22
	s_lshl_b32 s0, s80, 5
	s_sub_i32 s0, s0, s1
	v_writelane_b32 v255, s0, 23
	s_lshl_b32 s0, s4, 7
	s_lshl_b32 s1, s5, 10
	s_sub_i32 s0, s0, s1
	s_add_i32 s0, s0, 0xfff92000
	v_writelane_b32 v255, s0, 24
	s_lshl_b32 s0, s80, 10
	s_sub_i32 s0, s0, s1
	v_writelane_b32 v255, s0, 25
	s_lshl_b32 s0, s5, 3
	s_sub_i32 s1, s4, s0
	s_add_i32 s4, s1, 0xfffff240
	v_writelane_b32 v255, s4, 26
	s_mov_b32 s4, s74
	v_writelane_b32 v255, s4, 27
	s_sub_i32 s0, s74, s0
	s_xor_b64 s[2:3], s[2:3], -1
	v_writelane_b32 v255, s5, 28
	v_writelane_b32 v255, s0, 29
	s_add_i32 s0, s8, 0xfffc9000
	v_writelane_b32 v255, s0, 30
	s_add_i32 s0, s1, 0xfffff500
	v_writelane_b32 v255, s0, 31
	s_add_i32 s0, s1, 0xf500
	v_writelane_b32 v255, s0, 32
	v_writelane_b32 v255, s8, 33
	s_add_i32 s0, s8, 0xfffd4000
	v_writelane_b32 v255, s0, 34
	s_lshl_b32 s0, s80, 12
	s_lshl_b32 s1, s5, 12
	v_writelane_b32 v255, s5, 35
	s_sub_i32 s0, s0, s1
	v_writelane_b32 v255, s0, 36
	s_add_i32 s1, 0, 0x23fc0
	v_writelane_b32 v255, s1, 37
	s_add_i32 s1, 0, 0x23fc4
	v_writelane_b32 v255, s1, 38
	v_writelane_b32 v255, s2, 39
	s_lshl_b32 s44, s80, 6
	s_mov_b32 s5, 0x18000
	v_writelane_b32 v255, s3, 40
	v_writelane_b32 v255, s78, 41
	v_writelane_b32 v255, s82, 42
	s_mov_b32 s0, 0x50000
	v_mov_b64_e32 v[230:231], 0xff
	v_writelane_b32 v255, s83, 43
	s_mov_b32 s11, 0x41000000
	s_mov_b64 s[8:9], 0x40000
	s_mov_b64 s[70:71], 0x80
	s_mov_b64 s[62:63], 0x2000
	s_mov_b64 s[94:95], 0x20000
	s_mov_b64 s[72:73], 0x60000
	s_mov_b64 s[74:75], 0x80000
	s_mov_b64 s[66:67], 0xfe40000
	s_mov_b64 s[84:85], 0xfe40080
	s_mov_b32 s92, s91
	v_writelane_b32 v255, s79, 44
	s_barrier
	s_mov_b32 s98, 0
	s_mov_b32 s99, 0
	s_mov_b32 s100, 0
	s_cmpk_lg_i32 s80, 0x100
	s_cbranch_scc1 .Lgb_setup_done
	s_add_u32 s12, s42, 0x318000
	s_addc_u32 s13, s43, 0
	v_and_b32_e32 v2, 63, v244
	v_lshlrev_b32_e32 v3, 4, v2
	global_load_dwordx4 v[4:7], v3, s[12:13] sc1
	v_and_b32_e32 v8, 1, v2
	s_waitcnt vmcnt(0)
	v_readlane_b32 s1, v4, 0
	v_readlane_b32 s2, v5, 0
	v_readlane_b32 s3, v6, 0
	v_readlane_b32 s4, v7, 0
	v_readlane_b32 s16, v4, 1
	v_readlane_b32 s17, v5, 1
	v_readlane_b32 s18, v6, 1
	v_readlane_b32 s19, v7, 1
	v_cmp_eq_u32_e32 vcc, 1, v8
	s_nop 3
	v_mov_b32_e32 v9, s1
	v_mov_b32_e32 v10, s16
	v_cndmask_b32_e32 v9, v9, v10, vcc
	v_mov_b32_e32 v11, s2
	v_mov_b32_e32 v10, s17
	v_cndmask_b32_e32 v11, v11, v10, vcc
	v_mov_b32_e32 v12, s3
	v_mov_b32_e32 v10, s18
	v_cndmask_b32_e32 v12, v12, v10, vcc
	v_mov_b32_e32 v13, s4
	v_mov_b32_e32 v10, s19
	v_cndmask_b32_e32 v13, v13, v10, vcc
	v_xor_b32_e32 v9, v9, v4
	v_xor_b32_e32 v11, v11, v5
	v_xor_b32_e32 v12, v12, v6
	v_xor_b32_e32 v13, v13, v7
	v_or3_b32 v9, v9, v11, v12
	v_or_b32_e32 v9, v9, v13
	v_min_u32_e32 v10, v4, v5
	v_min3_u32 v10, v10, v6, v7
	v_cmp_ne_u32_e32 vcc, 0, v9
	v_cmp_eq_u32_e64 s[2:3], 0, v10
	s_nop 1
	s_or_b64 s[2:3], s[2:3], vcc
	s_cmp_lg_u64 s[2:3], 0
	s_cbranch_scc1 .Lgb_setup_done
	s_mov_b32 s98, 1
	v_readlane_b32 s4, v253, 1
	s_nop 3
	s_bfe_u32 s4, s4, 0x20001
	s_mul_i32 s4, s4, 1
	s_cmp_eq_u32 s4, 0
	s_cbranch_scc1 .Lgb_setup_done
